# weight conversions re-planned: tail blocks only in GEMM phases, remainder by all blocks at the end of phase 0
# speedup vs baseline: 1.1527x; 1.0038x over previous
.Lcv_entry:
	v_writelane_b32 v238, s4, 33
	v_writelane_b32 v238, s5, 34
	v_writelane_b32 v238, s6, 35
	v_writelane_b32 v238, s7, 36
	v_writelane_b32 v238, s8, 37
	v_writelane_b32 v238, s9, 38
	v_writelane_b32 v238, s10, 39
	v_writelane_b32 v238, s11, 40
	v_writelane_b32 v238, s12, 41
	v_writelane_b32 v238, s13, 42
	v_writelane_b32 v238, s14, 43
	v_writelane_b32 v238, s15, 44
	v_writelane_b32 v238, s16, 45
	v_writelane_b32 v238, s17, 46
	v_writelane_b32 v238, s18, 47
	v_writelane_b32 v238, s19, 48
	v_writelane_b32 v238, s20, 49
	v_writelane_b32 v238, s21, 50
	v_writelane_b32 v238, s22, 51
	v_writelane_b32 v238, s23, 52
	v_writelane_b32 v238, s24, 53
	v_writelane_b32 v238, s25, 54
	v_writelane_b32 v238, s26, 55
	v_writelane_b32 v238, s27, 56
	v_writelane_b32 v238, s28, 57
	v_writelane_b32 v238, s29, 58
	v_writelane_b32 v238, s30, 59
	v_writelane_b32 v238, s31, 60
	s_mov_b64 exec, -1
	v_readlane_b32 s4, v242, 1
	v_readlane_b32 s5, v242, 2
	v_readlane_b32 s6, v242, 0
	s_mov_b32 s7, s76
	s_nop 4
	s_load_dwordx2 s[8:9], s[4:5], 0xf8
	s_cmp_lg_u32 s100, 0
	s_cbranch_scc1 .Lcv_np_0
	s_movk_i32 s13, 0x0
	s_movk_i32 s14, 0x380
	s_movk_i32 s15, 0x4c0
	s_movk_i32 s16, 0xcc0
	s_movk_i32 s17, 0x100
	s_movk_i32 s18, 0x11a0
	s_movk_i32 s12, 0x5e0
	s_movk_i32 s10, 0
	s_branch .Lcv_plan_done
.Lcv_np_0:
	s_cmp_lg_u32 s100, 2
	s_cbranch_scc1 .Lcv_np_2
	s_movk_i32 s13, 0x580
	s_movk_i32 s14, 0xb00
	s_movk_i32 s15, 0x160
	s_movk_i32 s16, 0x1080
	s_movk_i32 s17, 0x120
	s_movk_i32 s18, 0x0
	s_movk_i32 s12, 0x280
	s_movk_i32 s10, 0
	s_branch .Lcv_plan_done
.Lcv_np_2:
	s_cmp_lg_u32 s100, 5
	s_cbranch_scc1 .Lcv_np_5
	s_movk_i32 s13, 0x3c0
	s_movk_i32 s14, 0x11c0
	s_movk_i32 s15, 0x80
	s_movk_i32 s16, 0x2c0
	s_movk_i32 s17, 0xc0
	s_movk_i32 s18, 0x0
	s_movk_i32 s12, 0x140
	s_movk_i32 s10, 0
	s_branch .Lcv_plan_done
.Lcv_np_5:
	s_cmp_lg_u32 s100, 10
	s_cbranch_scc1 .Lcv_np_10
	s_movk_i32 s13, 0x580
	s_movk_i32 s14, 0x8e0
	s_movk_i32 s15, 0x220
	s_movk_i32 s16, 0xc60
	s_movk_i32 s17, 0x60
	s_movk_i32 s18, 0x0
	s_movk_i32 s12, 0x280
	s_movk_i32 s10, 0
	s_branch .Lcv_plan_done
.Lcv_np_10:
	s_cmp_lg_u32 s100, 13
	s_cbranch_scc1 .Lcv_np_13
	s_movk_i32 s13, 0x580
	s_movk_i32 s14, 0xdc0
	s_movk_i32 s15, 0x160
	s_movk_i32 s16, 0x1240
	s_movk_i32 s17, 0x80
	s_movk_i32 s18, 0x840
	s_movk_i32 s12, 0x280
	s_movk_i32 s10, 0
	s_branch .Lcv_plan_done
.Lcv_np_13:
	s_cmp_lg_u32 s100, 20
	s_cbranch_scc1 .Lcv_np_20
	s_movk_i32 s13, 0x580
	s_movk_i32 s14, 0xf20
	s_movk_i32 s15, 0x160
	s_movk_i32 s16, 0x0
	s_movk_i32 s17, 0x0
	s_movk_i32 s18, 0x0
	s_movk_i32 s12, 0x160
	s_movk_i32 s10, 0
	s_branch .Lcv_plan_done
.Lcv_np_20:
	s_branch .Lcv_exit

.Lcv_ring:
	s_waitcnt lgkmcnt(0)
	s_mov_b32 s21, s20
	s_cmp_lt_u32 s21, s12
	s_cselect_b32 s13, s21, s20
	s_cselect_b32 vcc_hi, 1, 0
	s_mov_b32 s28, s13
	s_cmp_lt_u32 s28, s15
	s_cbranch_scc0 .Lcv_m1_1
	s_add_u32 s29, s14, s28
	s_branch .Lcv_m3_1

.Lcv_exit:
	s_waitcnt lgkmcnt(0)
	v_readlane_b32 s4, v238, 33
	v_readlane_b32 s5, v238, 34
	v_readlane_b32 s6, v238, 35
	v_readlane_b32 s7, v238, 36
	v_readlane_b32 s8, v238, 37
	v_readlane_b32 s9, v238, 38
	v_readlane_b32 s10, v238, 39
	v_readlane_b32 s11, v238, 40
	v_readlane_b32 s12, v238, 41
	v_readlane_b32 s13, v238, 42
	v_readlane_b32 s14, v238, 43
	v_readlane_b32 s15, v238, 44
	v_readlane_b32 s16, v238, 45
	v_readlane_b32 s17, v238, 46
	v_readlane_b32 s18, v238, 47
	v_readlane_b32 s19, v238, 48
	v_readlane_b32 s20, v238, 49
	v_readlane_b32 s21, v238, 50
	v_readlane_b32 s22, v238, 51
	v_readlane_b32 s23, v238, 52
	v_readlane_b32 s24, v238, 53
	v_readlane_b32 s25, v238, 54
	v_readlane_b32 s26, v238, 55
	v_readlane_b32 s27, v238, 56
	v_readlane_b32 s28, v238, 57
	v_readlane_b32 s29, v238, 58
	v_readlane_b32 s30, v238, 59
	v_readlane_b32 s31, v238, 60
	s_nop 4
	s_cmp_eq_u32 s100, 0
	s_cbranch_scc1 .Lcv_ret_p0
	s_cmp_eq_u32 s100, 5
	s_cbranch_scc1 .Lcv_ret_inp
	s_cmp_eq_u32 s100, 10
	s_cbranch_scc1 .Lcv_ret_gu2
	s_cmp_eq_u32 s100, 20
	s_cbranch_scc1 .Lcv_ret_gu2
	s_branch .Lcv_ret_gu1
.Lp0_hook:
	s_mov_b32 s100, 0
	s_branch .Lcv_entry
.Lcv_ret_p0:
	s_branch .Lp0_back
.LBB0_336:
	s_mov_b64 s[0:1], 0
	s_mov_b64 s[22:23], 0x36080
	s_mov_b64 s[24:25], 0x36100
	s_and_b64 vcc, exec, s[18:19]
	s_cbranch_vccnz .LBB0_1116
	s_branch .LBB0_1332

.LBB0_1641:
	s_or_b64 exec, exec, s[0:1]
	s_branch .Lp0_hook
.Lp0_back:
	s_add_i32 s20, s16, 1
	s_cmp_ge_i32 s20, s17
	s_cbranch_scc0 .LBB0_1413
